# WY producer: one static s_setprio 1 for waves 4-7 (the second-dispatched wave of each SIMD) for the duration of the task loop
# speedup vs baseline: 1.0053x; 1.0039x over previous
; __device__ __forceinline__ void p3b_wy_producer(const Ctx& c0, int l, int rep) {
;     ...
;     if (tk < 2048) {
;         WyPre P; wy_prefetch(c, P, l, tk, c.lane, c.wave);
;         for (;;) { const int tn = wy_producer_task(c, l, tk, P, head);
;             if (tn >= 2048) break;
;             tk = tn; }
;     }
;     ...
;     __syncthreads();
.LBB0_657:
	s_setprio 0
	v_readlane_b32 s28, v255, 0
	v_readlane_b32 s50, v255, 2
	v_readlane_b32 s54, v255, 4
	v_readlane_b32 s29, v255, 1
	v_readlane_b32 s27, v255, 18
	v_readlane_b32 s51, v255, 3
	v_readlane_b32 s55, v255, 5
	v_readlane_b32 s56, v255, 6
	v_readlane_b32 s57, v255, 8
	v_readlane_b32 s58, v255, 9

; #define LAS __attribute__((address_space(3)))
; __device__ __forceinline__ int wy_producer_task(const Ctx& c, int l, int tk, WyPre& P, unsigned* head) {
;     LAS float* Lf = (LAS float*)c.lds; LAS float* KF = Lf + WY_KF; LAS float* QF = Lf + WY_QF; LAS float* LM = Lf + WY_LM; LAS float* KT = Lf + WY_KT; LAS float* GC = Lf + WY_GC; LAS float* BE = Lf + WY_BE;
;     LAS unsigned char* KIMG = c.lds + WY_KIMG_B;
;     int lane = c.lane; asm volatile("" : "+v"(lane));
;     const int wid = c.wave, r32 = lane & 31, hi = lane >> 5, q4 = lane & 3, cc = lane >> 2;
;     const int hh = tk & 7;
;     u32x4* PKm = (u32x4*)(AWS + WS_PK);
;     volatile LAS unsigned* slot = (volatile LAS unsigned*)(c.lds - CTLB + MISC_OFF + 64);
;     unsigned gnext = 0u;
;     if (wid == 0 && lane == 0) gnext = __hip_atomic_fetch_add(head, 1u, __ATOMIC_RELAXED, __HIP_MEMORY_SCOPE_AGENT);
;     LAS float* VF = Lf + WY_VF;
; __device__ __forceinline__ void p3b_wy_producer(const Ctx& c0, int l, int rep) {
;     ...
;     if (tk < 2048) {
;         WyPre P; wy_prefetch(c, P, l, tk, c.lane, c.wave);
;         for (;;) { const int tn = wy_producer_task(c, l, tk, P, head);
;             if (tn >= 2048) break;
;             tk = tn; }
.LBB0_958:
	s_or_b32 s50, s93, 3
	s_or_b32 s51, s93, 4
	s_or_b32 s64, s93, 5
	s_or_b32 s65, s93, 6
	s_or_b32 s86, s93, 7
	s_lshl_b32 s1, s0, 6
	s_lshl_b32 s88, s0, 7
	s_lshl_b32 s60, s94, 4
	s_lshl_b32 s61, s95, 4
	s_lshl_b32 s91, s50, 4
	s_lshl_b32 s92, s51, 4
	s_lshl_b32 s62, s64, 4
	s_lshl_b32 s63, s65, 4
	s_lshl_b32 s89, s86, 4
	s_cmp_gt_i32 s0, 3
	v_sub_co_u32_e64 v2, s[2:3], s0, 6
	s_cselect_b64 s[74:75], -1, 0
	s_xor_b64 s[76:77], s[2:3], -1
	s_cmp_eq_u32 s0, 6
	s_cselect_b64 s[2:3], -1, 0
	v_writelane_b32 v255, s2, 20
	s_mul_i32 s96, s0, 0x820
	v_lshlrev_b32_e32 v3, 7, v2
	v_writelane_b32 v255, s3, 21
	s_add_i32 s2, s0, -4
	s_lshl_b32 s29, s2, 5
	s_lshl_b32 s2, s2, 8
	v_writelane_b32 v255, s2, 22
	s_and_b32 s2, s0, 1
	s_lshl_b32 s58, s2, 5
	s_cmp_gt_u32 s0, 1
	s_cselect_b64 s[80:81], -1, 0
	s_cmp_lt_u32 s0, 2
	s_movk_i32 s3, 0x4500
	s_cselect_b32 s3, 0x400, s3
	s_lshl_b32 s2, s2, 8
	v_writelane_b32 v255, s2, 23
	s_add_i32 s87, s1, 0
	s_add_i32 s79, s93, -3
	s_add_i32 s57, s93, -2
	s_add_i32 s54, s93, -1
	s_lshl_b32 s2, s0, 4
	s_add_i32 s59, s3, 0
	s_add_i32 s78, s87, 0x11d00
	s_ashr_i32 s56, s79, 31
	s_ashr_i32 s90, s57, 31
	s_ashr_i32 s55, s54, 31
	s_ashr_i32 s42, s93, 31
	s_ashr_i32 s43, s94, 31
	s_ashr_i32 s66, s95, 31
	s_ashr_i32 s67, s50, 31
	s_ashr_i32 s48, s51, 31
	s_ashr_i32 s49, s64, 31
	s_ashr_i32 s68, s65, 31
	s_ashr_i32 s69, s86, 31
	s_ashr_i32 s3, s2, 31
	s_cmp_lt_i32 s0, 2
	s_cselect_b64 s[82:83], -1, 0
	s_lshl_b32 s70, s0, 5
	s_lshl_b32 s71, s0, 8
	s_mov_b32 s0, 0x5040100
	s_mul_i32 s97, s94, 0x104
	v_add_u32_e32 v83, 0, v3
	v_lshlrev_b32_e32 v95, 8, v2
	s_waitcnt vmcnt(12)
	v_perm_b32 v89, v6, v5, s0
	v_perm_b32 v114, v4, v0, s0
	v_perm_b32 v115, v8, v7, s0
	v_perm_b32 v116, v10, v9, s0
	v_perm_b32 v117, v12, v11, s0
	s_waitcnt vmcnt(8)
	v_perm_b32 v118, v14, v17, s0
	v_perm_b32 v119, v13, v15, s0
	v_perm_b32 v120, v16, v19, s0
	v_perm_b32 v121, v18, v21, s0
	v_perm_b32 v122, v20, v22, s0
	s_lshl_b64 s[84:85], s[2:3], 2
	v_readlane_b32 s1, v254, 46
	s_cmp_gt_u32 s1, 3
	s_cbranch_scc0 .Lwp_prio
	s_setprio 1
.Lwp_prio:
	s_branch .LBB0_960
.LBB0_959:
	s_cmpk_lt_i32 s0, 0x800
	s_mov_b32 s46, s12
	s_cbranch_scc0 .LBB0_657
